# also: lora2 / gate tile loops without the duplicate tail K-tile DMAs (and without their drain)
# speedup vs baseline: 1.0394x; 1.0003x over previous
.LBB0_908:
	s_ashr_i32 s9, s39, 3
	s_lshl_b32 s1, s39, 8
	s_and_b32 s0, s39, 4
	s_lshl_b32 s40, s9, 8
	s_and_b32 s8, s1, 0x300
	s_bitcmp1_b32 s39, 2
	s_cselect_b64 s[10:11], -1, 0
	s_cmp_eq_u32 s0, 0
	s_cselect_b64 s[4:5], -1, 0
	s_and_b64 s[0:1], s[4:5], exec
	s_cselect_b32 s0, s3, 0xfd608c0
	s_cselect_b32 s1, s13, 0x928000
	s_add_u32 s6, s84, s0
	s_addc_u32 s7, s85, 0
	s_add_u32 s14, s84, s1
	s_addc_u32 s15, s85, 0
	v_mov_b32_e32 v10, v174
	s_cmp_lg_u32 s9, 64
	s_cselect_b64 s[0:1], -1, 0
	v_readfirstlane_b32 s16, v10
	s_ashr_i32 s17, s16, 6
	v_bfe_u32 v0, v10, 2, 4
	s_lshl_b32 s18, s17, 4
	v_or_b32_e32 v4, s40, v0
	s_add_i32 s19, s18, 0x80
	v_or_b32_e32 v0, s8, v0
	v_add_u32_e32 v6, s18, v0
	v_add_u32_e32 v8, s19, v0
	v_ashrrev_i32_e32 v7, 31, v6
	v_ashrrev_i32_e32 v9, 31, v8
	s_and_b32 s9, s17, 3
	v_add_u32_e32 v2, s18, v4
	v_add_u32_e32 v4, s19, v4
	v_lshlrev_b64 v[6:7], 7, v[6:7]
	v_lshlrev_b64 v[8:9], 7, v[8:9]
	s_ashr_i32 s16, s16, 8
	v_ashrrev_i32_e32 v3, 31, v2
	v_ashrrev_i32_e32 v5, 31, v4
	v_lshl_add_u64 v[6:7], s[14:15], 0, v[6:7]
	v_lshl_add_u64 v[8:9], s[14:15], 0, v[8:9]
	s_lshl_b32 s14, s16, 13
	s_lshl_b32 s15, s9, 12
	v_bfe_u32 v166, v10, 4, 2
	v_lshlrev_b64 v[2:3], 7, v[2:3]
	v_lshlrev_b64 v[4:5], 7, v[4:5]
	s_cmp_lg_u32 s16, 1
	v_bitop3_b32 v11, v166, v10, 3 bitop3:0x78
	v_lshl_add_u64 v[4:5], s[6:7], 0, v[4:5]
	v_lshl_add_u64 v[2:3], s[6:7], 0, v[2:3]
	s_cselect_b64 s[6:7], -1, 0
	s_lshl_b32 s18, s17, 10
	v_lshlrev_b32_e32 v0, 4, v11
	s_add_i32 s17, s18, 0
	v_lshl_add_u64 v[2:3], v[2:3], 0, v[0:1]
	s_mov_b32 m0, s17
	v_lshl_add_u64 v[4:5], v[4:5], 0, v[0:1]
	global_load_lds_dwordx4 v[2:3], off
	s_add_i32 m0, s17, 0x2000
	v_lshl_add_u64 v[6:7], v[6:7], 0, v[0:1]
	global_load_lds_dwordx4 v[4:5], off
	s_add_i32 m0, s17, 0x4000
	v_lshl_add_u64 v[8:9], v[8:9], 0, v[0:1]
	global_load_lds_dwordx4 v[6:7], off
	s_add_i32 m0, s17, 0x6000
	v_lshl_add_u64 v[158:159], v[2:3], 0, 64
	global_load_lds_dwordx4 v[8:9], off
	s_add_i32 m0, s17, 0x8000
	v_lshl_add_u64 v[160:161], v[4:5], 0, 64
	global_load_lds_dwordx4 v[158:159], off
	s_add_i32 m0, s17, 0xa000
	v_lshl_add_u64 v[162:163], v[6:7], 0, 64
	global_load_lds_dwordx4 v[160:161], off
	s_add_i32 m0, s17, 0xc000
	v_lshl_add_u64 v[164:165], v[8:9], 0, 64
	global_load_lds_dwordx4 v[162:163], off
	s_add_i32 m0, s17, 0xe000
	s_add_i32 s19, s18, 0x2000
	global_load_lds_dwordx4 v[164:165], off
	v_lshrrev_b32_e32 v0, 2, v10
	v_bitop3_b32 v0, v166, v0, 3 bitop3:0x78
	v_mov_b32_e32 v2, v1
	v_mov_b32_e32 v3, v1
	s_waitcnt vmcnt(4)
	s_or_b64 s[0:1], s[0:1], s[6:7]
	v_and_b32_e32 v167, 15, v10
	v_lshlrev_b32_e32 v168, 4, v0
	s_waitcnt lgkmcnt(0)
	s_barrier
	v_mov_b32_e32 v0, v1
	v_cndmask_b32_e64 v4, 0, 1, s[0:1]
	v_mov_b64_e32 v[20:21], v[2:3]
	v_mov_b64_e32 v[24:25], v[2:3]
	v_mov_b64_e32 v[28:29], v[2:3]
	v_mov_b64_e32 v[32:33], v[2:3]
	v_mov_b64_e32 v[36:37], v[2:3]
	v_mov_b64_e32 v[40:41], v[2:3]
	v_mov_b64_e32 v[44:45], v[2:3]
	v_mov_b64_e32 v[48:49], v[2:3]
	v_mov_b64_e32 v[52:53], v[2:3]
	v_mov_b64_e32 v[56:57], v[2:3]
	v_mov_b64_e32 v[60:61], v[2:3]
	v_mov_b64_e32 v[64:65], v[2:3]
	v_mov_b64_e32 v[68:69], v[2:3]
	v_mov_b64_e32 v[72:73], v[2:3]
	v_mov_b64_e32 v[76:77], v[2:3]
	v_mov_b64_e32 v[80:81], v[2:3]
	v_mov_b64_e32 v[84:85], v[2:3]
	v_mov_b64_e32 v[88:89], v[2:3]
	v_mov_b64_e32 v[92:93], v[2:3]
	v_mov_b64_e32 v[96:97], v[2:3]
	v_mov_b64_e32 v[100:101], v[2:3]
	v_mov_b64_e32 v[104:105], v[2:3]
	v_mov_b64_e32 v[108:109], v[2:3]
	v_mov_b64_e32 v[112:113], v[2:3]
	v_mov_b64_e32 v[116:117], v[2:3]
	v_mov_b64_e32 v[120:121], v[2:3]
	v_mov_b64_e32 v[124:125], v[2:3]
	v_mov_b64_e32 v[128:129], v[2:3]
	v_mov_b64_e32 v[16:17], v[2:3]
	v_mov_b64_e32 v[12:13], v[2:3]
	v_mov_b64_e32 v[8:9], v[2:3]
	v_cmp_ne_u32_e64 s[0:1], 1, v4
	v_mov_b64_e32 v[18:19], v[0:1]
	v_mov_b64_e32 v[22:23], v[0:1]
	v_mov_b64_e32 v[26:27], v[0:1]
	v_mov_b64_e32 v[30:31], v[0:1]
	v_mov_b64_e32 v[34:35], v[0:1]
	v_mov_b64_e32 v[38:39], v[0:1]
	v_mov_b64_e32 v[42:43], v[0:1]
	v_mov_b64_e32 v[46:47], v[0:1]
	v_mov_b64_e32 v[50:51], v[0:1]
	v_mov_b64_e32 v[54:55], v[0:1]
	v_mov_b64_e32 v[58:59], v[0:1]
	v_mov_b64_e32 v[62:63], v[0:1]
	v_mov_b64_e32 v[66:67], v[0:1]
	v_mov_b64_e32 v[70:71], v[0:1]
	v_mov_b64_e32 v[74:75], v[0:1]
	v_mov_b64_e32 v[78:79], v[0:1]
	v_mov_b64_e32 v[82:83], v[0:1]
	v_mov_b64_e32 v[86:87], v[0:1]
	v_mov_b64_e32 v[90:91], v[0:1]
	v_mov_b64_e32 v[94:95], v[0:1]
	v_mov_b64_e32 v[98:99], v[0:1]
	v_mov_b64_e32 v[102:103], v[0:1]
	v_mov_b64_e32 v[106:107], v[0:1]
	v_mov_b64_e32 v[110:111], v[0:1]
	v_mov_b64_e32 v[114:115], v[0:1]
	v_mov_b64_e32 v[118:119], v[0:1]
	v_mov_b64_e32 v[122:123], v[0:1]
	v_mov_b64_e32 v[126:127], v[0:1]
	v_mov_b64_e32 v[14:15], v[0:1]
	v_mov_b64_e32 v[10:11], v[0:1]
	v_mov_b64_e32 v[6:7], v[0:1]
	v_mov_b64_e32 v[4:5], v[2:3]
	v_lshlrev_b32_e32 v169, 6, v167
	v_mov_b64_e32 v[2:3], v[0:1]
	s_mov_b64 s[6:7], -1
	s_mov_b32 s18, 0
	s_branch .LBB0_910
.LBB0_909:
	s_waitcnt vmcnt(0)
	s_waitcnt lgkmcnt(0)
	s_barrier
	s_xor_b64 s[42:43], s[6:7], -1
	s_mov_b32 s18, 0x8000
	s_mov_b64 s[6:7], 0
	s_and_b64 vcc, exec, s[42:43]
	s_cbranch_vccnz .LBB0_912
.LBB0_910:
	s_add_i32 s19, s18, 0
	s_add_i32 s41, s19, s15
	s_add_i32 s18, s18, 0x18000
	v_add3_u32 v0, s41, v169, v168
	s_add_i32 s19, s19, s14
	s_and_b32 s18, s18, 0x18000
	s_waitcnt lgkmcnt(0)
	ds_read_b128 v[130:133], v0 offset:16384
	ds_read_b128 v[134:137], v0 offset:17408
	ds_read_b128 v[138:141], v0 offset:18432
	ds_read_b128 v[142:145], v0 offset:19456
	v_add_u32_e32 v0, s19, v169
	s_add_i32 s18, s17, s18
	v_add_u32_e32 v0, v0, v168
	ds_read_b128 v[154:157], v0
	ds_read_b128 v[150:153], v0 offset:1024
	ds_read_b128 v[146:149], v0 offset:2048
	s_and_b64 vcc, exec, s[0:1]
	s_cbranch_vccnz .LBB0_909
	s_waitcnt lgkmcnt(0)
	v_mfma_f32_16x16x32_bf16 v[126:129], v[130:133], v[154:157], v[126:129]
	ds_read_b128 v[170:173], v0 offset:3072
	v_mfma_f32_16x16x32_bf16 v[122:125], v[134:137], v[154:157], v[122:125]
	v_mfma_f32_16x16x32_bf16 v[118:121], v[138:141], v[154:157], v[118:121]
	v_mfma_f32_16x16x32_bf16 v[114:117], v[142:145], v[154:157], v[114:117]
	v_mfma_f32_16x16x32_bf16 v[110:113], v[130:133], v[150:153], v[110:113]
	ds_read_b128 v[154:157], v0 offset:4096
	v_mfma_f32_16x16x32_bf16 v[106:109], v[134:137], v[150:153], v[106:109]
	v_mfma_f32_16x16x32_bf16 v[102:105], v[138:141], v[150:153], v[102:105]
	v_mfma_f32_16x16x32_bf16 v[98:101], v[142:145], v[150:153], v[98:101]
	v_mfma_f32_16x16x32_bf16 v[94:97], v[130:133], v[146:149], v[94:97]
	ds_read_b128 v[150:153], v0 offset:5120
	v_mfma_f32_16x16x32_bf16 v[90:93], v[134:137], v[146:149], v[90:93]
	v_mfma_f32_16x16x32_bf16 v[86:89], v[138:141], v[146:149], v[86:89]
	v_mfma_f32_16x16x32_bf16 v[82:85], v[142:145], v[146:149], v[82:85]
	s_waitcnt lgkmcnt(0)
	v_mfma_f32_16x16x32_bf16 v[78:81], v[130:133], v[170:173], v[78:81]
	ds_read_b128 v[146:149], v0 offset:6144
	v_mfma_f32_16x16x32_bf16 v[74:77], v[134:137], v[170:173], v[74:77]
	v_mfma_f32_16x16x32_bf16 v[70:73], v[138:141], v[170:173], v[70:73]
	v_mfma_f32_16x16x32_bf16 v[66:69], v[142:145], v[170:173], v[66:69]
	v_mfma_f32_16x16x32_bf16 v[62:65], v[130:133], v[154:157], v[62:65]
	ds_read_b128 v[170:173], v0 offset:7168
	v_mfma_f32_16x16x32_bf16 v[58:61], v[134:137], v[154:157], v[58:61]
	v_mfma_f32_16x16x32_bf16 v[54:57], v[138:141], v[154:157], v[54:57]
	v_mfma_f32_16x16x32_bf16 v[50:53], v[142:145], v[154:157], v[50:53]
	v_mfma_f32_16x16x32_bf16 v[46:49], v[130:133], v[150:153], v[46:49]
	v_mfma_f32_16x16x32_bf16 v[42:45], v[134:137], v[150:153], v[42:45]
	v_mfma_f32_16x16x32_bf16 v[38:41], v[138:141], v[150:153], v[38:41]
	v_mfma_f32_16x16x32_bf16 v[34:37], v[142:145], v[150:153], v[34:37]
	s_waitcnt lgkmcnt(0)
	v_mfma_f32_16x16x32_bf16 v[30:33], v[130:133], v[146:149], v[30:33]
	v_mfma_f32_16x16x32_bf16 v[26:29], v[134:137], v[146:149], v[26:29]
	v_mfma_f32_16x16x32_bf16 v[22:25], v[138:141], v[146:149], v[22:25]
	v_mfma_f32_16x16x32_bf16 v[18:21], v[142:145], v[146:149], v[18:21]
	v_mfma_f32_16x16x32_bf16 v[14:17], v[130:133], v[170:173], v[14:17]
	v_mfma_f32_16x16x32_bf16 v[10:13], v[134:137], v[170:173], v[10:13]
	v_mfma_f32_16x16x32_bf16 v[6:9], v[138:141], v[170:173], v[6:9]
	v_mfma_f32_16x16x32_bf16 v[2:5], v[142:145], v[170:173], v[2:5]
	s_branch .LBB0_909

.LBB0_1248:
	s_cmp_eq_u32 s22, 0
	s_cbranch_scc1 .Lnd2g_w8
	s_waitcnt vmcnt(0)
	s_branch .Lnd2g_wd

.Lnd2g_wd:
	s_waitcnt lgkmcnt(0)
	s_barrier
	s_add_i32 s22, s22, 0x8000
	s_cmp_eq_u32 s22, 0x20000
	s_cbranch_scc1 .LBB0_1251
.LBB0_1249:
	s_add_i32 s23, s22, 0x18000
	s_and_b32 s23, s23, 0x18000
	v_add_u32_e32 v0, s22, v172
	s_add_i32 s23, s21, s23
	s_waitcnt lgkmcnt(0)
	ds_read_b128 v[130:133], v0
	ds_read_b128 v[134:137], v0 offset:1024
	ds_read_b128 v[138:141], v0 offset:2048
	ds_read_b128 v[142:145], v0 offset:3072
	v_add_u32_e32 v0, s22, v171
	ds_read_b128 v[154:157], v0
	ds_read_b128 v[150:153], v0 offset:1024
	ds_read_b128 v[146:149], v0 offset:2048
	s_and_b64 vcc, exec, s[0:1]
	s_cmp_eq_u32 s22, 0
	s_cbranch_scc0 .Lnd2g_skip
	s_mov_b32 m0, s23
	s_nop 0
	global_load_lds_dwordx4 v[158:159], off
	s_add_i32 m0, s23, 0x2000
	s_nop 0
	global_load_lds_dwordx4 v[160:161], off
	s_add_i32 m0, s23, 0x4000
	s_nop 0
	global_load_lds_dwordx4 v[162:163], off
	s_add_i32 m0, s23, 0x6000
	s_nop 0
	global_load_lds_dwordx4 v[164:165], off
.Lnd2g_skip:
	s_cbranch_vccnz .LBB0_1248
	s_waitcnt lgkmcnt(0)
	v_mfma_f32_16x16x32_bf16 v[126:129], v[130:133], v[154:157], v[126:129]
	ds_read_b128 v[176:179], v0 offset:3072
	v_mfma_f32_16x16x32_bf16 v[122:125], v[134:137], v[154:157], v[122:125]
	v_mfma_f32_16x16x32_bf16 v[118:121], v[138:141], v[154:157], v[118:121]
	v_mfma_f32_16x16x32_bf16 v[114:117], v[142:145], v[154:157], v[114:117]
	v_mfma_f32_16x16x32_bf16 v[110:113], v[130:133], v[150:153], v[110:113]
	ds_read_b128 v[154:157], v0 offset:4096
	v_mfma_f32_16x16x32_bf16 v[106:109], v[134:137], v[150:153], v[106:109]
	v_mfma_f32_16x16x32_bf16 v[102:105], v[138:141], v[150:153], v[102:105]
	v_mfma_f32_16x16x32_bf16 v[98:101], v[142:145], v[150:153], v[98:101]
	v_mfma_f32_16x16x32_bf16 v[94:97], v[130:133], v[146:149], v[94:97]
	ds_read_b128 v[150:153], v0 offset:5120
	v_mfma_f32_16x16x32_bf16 v[90:93], v[134:137], v[146:149], v[90:93]
	v_mfma_f32_16x16x32_bf16 v[86:89], v[138:141], v[146:149], v[86:89]
	v_mfma_f32_16x16x32_bf16 v[82:85], v[142:145], v[146:149], v[82:85]
	s_waitcnt lgkmcnt(0)
	v_mfma_f32_16x16x32_bf16 v[78:81], v[130:133], v[176:179], v[78:81]
	ds_read_b128 v[146:149], v0 offset:6144
	v_mfma_f32_16x16x32_bf16 v[74:77], v[134:137], v[176:179], v[74:77]
	v_mfma_f32_16x16x32_bf16 v[70:73], v[138:141], v[176:179], v[70:73]
	v_mfma_f32_16x16x32_bf16 v[66:69], v[142:145], v[176:179], v[66:69]
	v_mfma_f32_16x16x32_bf16 v[62:65], v[130:133], v[154:157], v[62:65]
	ds_read_b128 v[176:179], v0 offset:7168
	v_mfma_f32_16x16x32_bf16 v[58:61], v[134:137], v[154:157], v[58:61]
	v_mfma_f32_16x16x32_bf16 v[54:57], v[138:141], v[154:157], v[54:57]
	v_mfma_f32_16x16x32_bf16 v[50:53], v[142:145], v[154:157], v[50:53]
	v_mfma_f32_16x16x32_bf16 v[46:49], v[130:133], v[150:153], v[46:49]
	v_mfma_f32_16x16x32_bf16 v[42:45], v[134:137], v[150:153], v[42:45]
	v_mfma_f32_16x16x32_bf16 v[38:41], v[138:141], v[150:153], v[38:41]
	v_mfma_f32_16x16x32_bf16 v[34:37], v[142:145], v[150:153], v[34:37]
	s_waitcnt lgkmcnt(0)
	v_mfma_f32_16x16x32_bf16 v[30:33], v[130:133], v[146:149], v[30:33]
	v_mfma_f32_16x16x32_bf16 v[26:29], v[134:137], v[146:149], v[26:29]
	v_mfma_f32_16x16x32_bf16 v[22:25], v[138:141], v[146:149], v[22:25]
	v_mfma_f32_16x16x32_bf16 v[18:21], v[142:145], v[146:149], v[18:21]
	v_mfma_f32_16x16x32_bf16 v[14:17], v[130:133], v[176:179], v[14:17]
	v_mfma_f32_16x16x32_bf16 v[10:13], v[134:137], v[176:179], v[10:13]
	v_mfma_f32_16x16x32_bf16 v[6:9], v[138:141], v[176:179], v[6:9]
	v_mfma_f32_16x16x32_bf16 v[2:5], v[142:145], v[176:179], v[2:5]
	s_branch .LBB0_1248
